# dn_pre: conv-weight loads hoisted above the activation-load wait (1 round trip per section instead of 3)
# speedup vs baseline: 1.0317x; 1.0044x over previous
.LBB0_338:
	s_or_b64 exec, exec, s[54:55]
	v_lshlrev_b32_e32 v228, 2, v45
	global_load_dwordx4 v[204:207], v228, s[44:45] offset:16
	global_load_dwordx4 v[208:211], v228, s[44:45]
	global_load_dwordx4 v[212:215], v228, s[48:49] offset:16
	global_load_dwordx4 v[216:219], v228, s[48:49]
	global_load_dwordx4 v[220:223], v228, s[50:51] offset:16
	global_load_dwordx4 v[224:227], v228, s[50:51]
	v_ashrrev_i32_e32 v13, 31, v12
	v_lshlrev_b64 v[12:13], 11, v[12:13]
	v_lshl_add_u64 v[12:13], s[4:5], 0, v[12:13]
	v_lshlrev_b32_e32 v128, 1, v14
	v_lshl_add_u64 v[12:13], v[12:13], 0, v[128:129]
	v_mov_b32_e32 v27, v129
	v_lshl_add_u64 v[28:29], v[12:13], 0, v[26:27]
	v_lshlrev_b32_e32 v27, 2, v45
	s_waitcnt vmcnt(6)
	v_lshlrev_b32_e32 v12, 16, v8
	v_lshlrev_b32_e32 v14, 16, v4
	v_and_b32_e32 v40, 0xffff0000, v8
	v_and_b32_e32 v54, 0xffff0000, v4
	v_lshlrev_b32_e32 v13, 16, v9
	v_lshlrev_b32_e32 v15, 16, v5
	v_and_b32_e32 v41, 0xffff0000, v9
	v_and_b32_e32 v55, 0xffff0000, v5
	v_lshlrev_b32_e32 v36, 16, v10
	v_lshlrev_b32_e32 v38, 16, v6
	v_and_b32_e32 v30, 0xffff0000, v10
	v_and_b32_e32 v32, 0xffff0000, v6
	v_lshlrev_b32_e32 v37, 16, v11
	v_lshlrev_b32_e32 v39, 16, v7
	v_and_b32_e32 v31, 0xffff0000, v11
	v_and_b32_e32 v33, 0xffff0000, v7
	v_lshlrev_b32_e32 v57, 16, v1
	v_lshlrev_b32_e32 v56, 16, v0
	v_and_b32_e32 v1, 0xffff0000, v1
	v_and_b32_e32 v0, 0xffff0000, v0
	s_waitcnt vmcnt(4)
	v_mov_b32_e32 v4, v204
	v_mov_b32_e32 v5, v205
	v_mov_b32_e32 v6, v206
	v_mov_b32_e32 v7, v207
	v_mov_b32_e32 v46, v208
	v_mov_b32_e32 v47, v209
	v_mov_b32_e32 v48, v210
	v_mov_b32_e32 v49, v211
	v_mov_b32_e32 v16, v46
	s_waitcnt vmcnt(2)
	v_mov_b32_e32 v8, v212
	v_mov_b32_e32 v9, v213
	v_mov_b32_e32 v10, v214
	v_mov_b32_e32 v11, v215
	v_mov_b32_e32 v50, v216
	v_mov_b32_e32 v51, v217
	v_mov_b32_e32 v52, v218
	v_mov_b32_e32 v53, v219
	v_mov_b32_e32 v18, v50
	v_mov_b32_e32 v19, v52
	v_mov_b32_e32 v17, v48
	v_pk_mul_f32 v[14:15], v[18:19], v[14:15]
	v_mov_b32_e32 v52, v51
	v_pk_fma_f32 v[34:35], v[16:17], v[12:13], v[14:15]
	s_waitcnt vmcnt(0)
	v_mov_b32_e32 v12, v220
	v_mov_b32_e32 v13, v221
	v_mov_b32_e32 v14, v222
	v_mov_b32_e32 v15, v223
	v_mov_b32_e32 v16, v224
	v_mov_b32_e32 v17, v225
	v_mov_b32_e32 v18, v226
	v_mov_b32_e32 v19, v227
	v_mov_b32_e32 v58, v16
	v_mov_b32_e32 v59, v18
	v_pk_fma_f32 v[34:35], v[58:59], v[56:57], v[34:35]
	s_nop 0
	v_mul_f32_e32 v16, 0xbfb8aa3b, v34
	v_exp_f32_e32 v56, v16
	v_mul_f32_e32 v16, 0xbfb8aa3b, v35
	v_exp_f32_e32 v57, v16
	s_nop 0
	v_pk_add_f32 v[56:57], v[56:57], 1.0 op_sel_hi:[1,0]
	s_nop 0
	v_div_scale_f32 v16, s[30:31], v57, v57, v35
	v_rcp_f32_e32 v18, v16
	s_nop 0
	v_fma_f32 v27, -v16, v18, 1.0
	v_fmac_f32_e32 v18, v27, v18
	v_div_scale_f32 v27, vcc, v35, v57, v35
	v_mul_f32_e32 v46, v27, v18
	v_fma_f32 v48, -v16, v46, v27
	v_fmac_f32_e32 v46, v48, v18
	v_fma_f32 v16, -v16, v46, v27
	v_div_fmas_f32 v16, v16, v18, v46
	v_div_fixup_f32 v35, v16, v57, v35
	v_div_scale_f32 v16, s[30:31], v56, v56, v34
	v_rcp_f32_e32 v18, v16
	s_nop 0
	v_fma_f32 v27, -v16, v18, 1.0
	v_fmac_f32_e32 v18, v27, v18
	v_div_scale_f32 v27, vcc, v34, v56, v34
	v_mul_f32_e32 v46, v27, v18
	v_fma_f32 v48, -v16, v46, v27
	v_fmac_f32_e32 v46, v48, v18
	v_fma_f32 v16, -v16, v46, v27
	v_div_fmas_f32 v16, v16, v18, v46
	v_mov_b32_e32 v48, v47
	v_pk_mul_f32 v[46:47], v[52:53], v[54:55]
	v_mov_b32_e32 v18, v17
	v_pk_fma_f32 v[40:41], v[48:49], v[40:41], v[46:47]
	v_div_fixup_f32 v34, v16, v56, v34
	v_pk_fma_f32 v[0:1], v[18:19], v[0:1], v[40:41]
	v_mov_b32_e32 v46, v8
	v_mul_f32_e32 v16, 0xbfb8aa3b, v0
	v_mul_f32_e32 v17, 0xbfb8aa3b, v1
	v_exp_f32_e32 v16, v16
	v_exp_f32_e32 v17, v17
	v_mov_b32_e32 v47, v10
	v_pk_mul_f32 v[38:39], v[46:47], v[38:39]
	v_pk_add_f32 v[16:17], v[16:17], 1.0 op_sel_hi:[1,0]
	s_nop 0
	v_div_scale_f32 v18, s[30:31], v17, v17, v1
	v_rcp_f32_e32 v19, v18
	s_nop 0
	v_fma_f32 v27, -v18, v19, 1.0
	v_fmac_f32_e32 v19, v27, v19
	v_div_scale_f32 v27, vcc, v1, v17, v1
	v_mul_f32_e32 v40, v27, v19
	v_fma_f32 v41, -v18, v40, v27
	v_fmac_f32_e32 v40, v41, v19
	v_fma_f32 v18, -v18, v40, v27
	v_div_fmas_f32 v18, v18, v19, v40
	v_div_fixup_f32 v1, v18, v17, v1
	v_div_scale_f32 v17, s[30:31], v16, v16, v0
	v_rcp_f32_e32 v18, v17
	v_mov_b32_e32 v41, v6
	v_fma_f32 v19, -v17, v18, 1.0
	v_fmac_f32_e32 v18, v19, v18
	v_div_scale_f32 v19, vcc, v0, v16, v0
	v_mul_f32_e32 v27, v19, v18
	v_fma_f32 v40, -v17, v27, v19
	v_fmac_f32_e32 v27, v40, v18
	v_mov_b32_e32 v40, v4
	v_pk_fma_f32 v[36:37], v[40:41], v[36:37], v[38:39]
	v_lshlrev_b32_e32 v39, 16, v3
	v_lshlrev_b32_e32 v38, 16, v2
	v_mov_b32_e32 v40, v12
	v_mov_b32_e32 v41, v14
	v_pk_fma_f32 v[36:37], v[40:41], v[38:39], v[36:37]
	v_fma_f32 v17, -v17, v27, v19
	v_mul_f32_e32 v4, 0xbfb8aa3b, v36
	v_exp_f32_e32 v38, v4
	v_mul_f32_e32 v4, 0xbfb8aa3b, v37
	v_exp_f32_e32 v39, v4
	v_div_fmas_f32 v17, v17, v18, v27
	v_and_b32_e32 v3, 0xffff0000, v3
	v_and_b32_e32 v2, 0xffff0000, v2
	v_pk_add_f32 v[38:39], v[38:39], 1.0 op_sel_hi:[1,0]
	v_mov_b32_e32 v14, v13
	v_div_scale_f32 v4, s[30:31], v39, v39, v37
	v_rcp_f32_e32 v6, v4
	v_div_fixup_f32 v0, v17, v16, v0
	v_mov_b32_e32 v16, v34
	v_mov_b32_e32 v17, v0
	v_fma_f32 v8, -v4, v6, 1.0
	v_fmac_f32_e32 v6, v8, v6
	v_div_scale_f32 v8, vcc, v37, v39, v37
	v_mul_f32_e32 v10, v8, v6
	v_fma_f32 v12, -v4, v10, v8
	v_fmac_f32_e32 v10, v12, v6
	v_fma_f32 v4, -v4, v10, v8
	v_div_fmas_f32 v4, v4, v6, v10
	v_div_fixup_f32 v37, v4, v39, v37
	v_div_scale_f32 v4, s[30:31], v38, v38, v36
	v_rcp_f32_e32 v6, v4
	v_pk_mul_f32 v[16:17], v[16:17], v[16:17]
	v_mov_b32_e32 v18, v35
	v_mov_b32_e32 v19, v1
	v_fma_f32 v8, -v4, v6, 1.0
	v_fmac_f32_e32 v6, v8, v6
	v_div_scale_f32 v8, vcc, v36, v38, v36
	v_mul_f32_e32 v10, v8, v6
	v_fma_f32 v12, -v4, v10, v8
	v_fmac_f32_e32 v10, v12, v6
	v_fma_f32 v4, -v4, v10, v8
	v_div_fmas_f32 v4, v4, v6, v10
	v_mov_b32_e32 v10, v9
	v_div_fixup_f32 v36, v4, v38, v36
	v_mov_b32_e32 v6, v5
	v_pk_mul_f32 v[4:5], v[10:11], v[32:33]
	v_pk_mul_f32 v[18:19], v[18:19], v[18:19]
	v_pk_fma_f32 v[4:5], v[6:7], v[30:31], v[4:5]
	v_mov_b32_e32 v11, 0
	v_pk_fma_f32 v[2:3], v[14:15], v[2:3], v[4:5]
	s_nop 0
	v_mul_f32_e32 v4, 0xbfb8aa3b, v2
	v_mul_f32_e32 v5, 0xbfb8aa3b, v3
	v_exp_f32_e32 v4, v4
	v_exp_f32_e32 v5, v5
	s_nop 0
	v_pk_add_f32 v[4:5], v[4:5], 1.0 op_sel_hi:[1,0]
	s_nop 0
	v_div_scale_f32 v6, s[30:31], v5, v5, v3
	v_rcp_f32_e32 v7, v6
	s_nop 0
	v_fma_f32 v8, -v6, v7, 1.0
	v_fmac_f32_e32 v7, v8, v7
	v_div_scale_f32 v8, vcc, v3, v5, v3
	v_mul_f32_e32 v9, v8, v7
	v_fma_f32 v10, -v6, v9, v8
	v_fmac_f32_e32 v9, v10, v7
	v_fma_f32 v6, -v6, v9, v8
	v_div_fmas_f32 v6, v6, v7, v9
	v_div_fixup_f32 v3, v6, v5, v3
	v_div_scale_f32 v5, s[30:31], v4, v4, v2
	v_rcp_f32_e32 v6, v5
	s_mov_b64 s[30:31], 0x800
	v_lshl_add_u64 v[12:13], v[22:23], 0, s[30:31]
	v_mov_b32_e32 v10, 0
	v_fma_f32 v7, -v5, v6, 1.0
	v_fmac_f32_e32 v6, v7, v6
	v_div_scale_f32 v7, vcc, v2, v4, v2
	v_mul_f32_e32 v8, v7, v6
	v_fma_f32 v9, -v5, v8, v7
	v_fmac_f32_e32 v8, v9, v6
	v_fma_f32 v5, -v5, v8, v7
	v_div_fmas_f32 v5, v5, v6, v8
	v_div_fixup_f32 v2, v5, v4, v2
	v_add_f32_e32 v8, v16, v17
	v_mov_b32_e32 v4, v36
	v_mov_b32_e32 v5, v2
	v_add_f32_e32 v8, v8, v18
	v_pk_mul_f32 v[4:5], v[4:5], v[4:5]
	v_add_f32_e32 v8, v8, v19
	v_mov_b32_e32 v6, v37
	v_mov_b32_e32 v7, v3
	v_add_f32_e32 v4, v8, v4
	v_pk_mul_f32 v[6:7], v[6:7], v[6:7]
	v_add_f32_e32 v4, v4, v5
	v_add_f32_e32 v4, v4, v6
	v_add_f32_e32 v4, v4, v7
	s_nop 1
	v_add_f32_dpp v4, v4, v4 quad_perm:[1,0,3,2] row_mask:0xf bank_mask:0xf bound_ctrl:1
	s_nop 1
	v_add_f32_dpp v4, v4, v4 quad_perm:[2,3,0,1] row_mask:0xf bank_mask:0xf bound_ctrl:1
	s_nop 1
	v_add_f32_dpp v4, v4, v4 row_half_mirror row_mask:0xf bank_mask:0xf bound_ctrl:1
	s_nop 1
	v_add_f32_dpp v4, v4, v4 row_mirror row_mask:0xf bank_mask:0xf bound_ctrl:1
	v_add_f32_e32 v4, 0x358637bd, v4
	v_cmp_gt_f32_e32 vcc, s95, v4
	v_mul_f32_e32 v5, 0x4b800000, v4
	s_nop 0
	v_cndmask_b32_e32 v4, v4, v5, vcc
	v_rsq_f32_e32 v4, v4
	s_nop 0
	v_mul_f32_e32 v5, 0x45800000, v4
	v_cndmask_b32_e32 v4, v4, v5, vcc
	v_mul_f32_e32 v4, 0x3db504f3, v4
	v_pk_mul_f32 v[2:3], v[2:3], v[4:5] op_sel_hi:[1,0]
	v_pk_mul_f32 v[6:7], v[36:37], v[4:5] op_sel_hi:[1,0]
	v_pk_mul_f32 v[0:1], v[0:1], v[4:5] op_sel_hi:[1,0]
	v_pk_mul_f32 v[4:5], v[34:35], v[4:5] op_sel_hi:[1,0]
	s_nop 0
	v_and_b32_sdwa v8, v5, v150 dst_sel:DWORD dst_unused:UNUSED_PAD src0_sel:WORD_1 src1_sel:DWORD
	v_and_b32_sdwa v9, v4, v150 dst_sel:DWORD dst_unused:UNUSED_PAD src0_sel:WORD_1 src1_sel:DWORD
	v_add3_u32 v5, v5, v8, s26
	v_and_b32_sdwa v8, v1, v150 dst_sel:DWORD dst_unused:UNUSED_PAD src0_sel:WORD_1 src1_sel:DWORD
	v_add3_u32 v4, v4, v9, s26
	v_and_b32_sdwa v9, v0, v150 dst_sel:DWORD dst_unused:UNUSED_PAD src0_sel:WORD_1 src1_sel:DWORD
	v_add3_u32 v1, v1, v8, s26
	v_add3_u32 v0, v0, v9, s26
	v_and_b32_e32 v1, 0xffff0000, v1
	v_and_b32_e32 v0, 0xffff0000, v0
	v_or_b32_sdwa v1, v1, v5 dst_sel:DWORD dst_unused:UNUSED_PAD src0_sel:DWORD src1_sel:WORD_1
	v_and_b32_sdwa v5, v6, v150 dst_sel:DWORD dst_unused:UNUSED_PAD src0_sel:WORD_1 src1_sel:DWORD
	v_or_b32_sdwa v0, v0, v4 dst_sel:DWORD dst_unused:UNUSED_PAD src0_sel:DWORD src1_sel:WORD_1
	v_and_b32_sdwa v4, v7, v150 dst_sel:DWORD dst_unused:UNUSED_PAD src0_sel:WORD_1 src1_sel:DWORD
	v_add3_u32 v5, v6, v5, s26
	v_and_b32_sdwa v6, v3, v150 dst_sel:DWORD dst_unused:UNUSED_PAD src0_sel:WORD_1 src1_sel:DWORD
	v_add3_u32 v4, v7, v4, s26
	v_and_b32_sdwa v7, v2, v150 dst_sel:DWORD dst_unused:UNUSED_PAD src0_sel:WORD_1 src1_sel:DWORD
	v_add3_u32 v3, v3, v6, s26
	v_add3_u32 v2, v2, v7, s26
	v_and_b32_e32 v3, 0xffff0000, v3
	v_and_b32_e32 v2, 0xffff0000, v2
	v_or_b32_sdwa v3, v3, v4 dst_sel:DWORD dst_unused:UNUSED_PAD src0_sel:DWORD src1_sel:WORD_1
	v_add_co_u32_e32 v4, vcc, 0x24000000, v28
	v_or_b32_sdwa v2, v2, v5 dst_sel:DWORD dst_unused:UNUSED_PAD src0_sel:DWORD src1_sel:WORD_1
	s_nop 0
	v_addc_co_u32_e32 v5, vcc, 0, v29, vcc
	global_store_dwordx4 v[4:5], v[0:3], off
	global_load_dwordx4 v[4:7], v[22:23], off offset:2048
	v_mov_b32_e32 v8, 0
	v_mov_b32_e32 v0, 0
	v_mov_b32_e32 v9, 0
	s_and_saveexec_b64 s[54:55], s[40:41]
	s_cbranch_execz .LBB0_340
	v_add_co_u32_e32 v2, vcc, 0xffffd000, v12
	s_nop 1
	v_addc_co_u32_e32 v3, vcc, -1, v13, vcc
	global_load_dwordx4 v[8:11], v[2:3], off offset:-2560

.LBB0_342:
	s_or_b64 exec, exec, s[54:55]
	v_mov_b32_e32 v229, 0x1000
	v_lshl_or_b32 v228, v45, 2, v229
	global_load_dwordx4 v[204:207], v228, s[44:45] offset:16
	global_load_dwordx4 v[208:211], v228, s[44:45]
	global_load_dwordx4 v[212:215], v228, s[48:49] offset:16
	global_load_dwordx4 v[216:219], v228, s[48:49]
	global_load_dwordx4 v[220:223], v228, s[50:51] offset:16
	global_load_dwordx4 v[224:227], v228, s[50:51]
	v_mov_b32_e32 v12, 0x1000
	v_lshl_or_b32 v27, v45, 2, v12
	s_waitcnt vmcnt(6)
	v_lshlrev_b32_e32 v12, 16, v8
	v_lshlrev_b32_e32 v14, 16, v4
	v_and_b32_e32 v50, 0xffff0000, v8
	v_and_b32_e32 v52, 0xffff0000, v4
	v_lshlrev_b32_e32 v13, 16, v9
	v_lshlrev_b32_e32 v15, 16, v5
	v_and_b32_e32 v51, 0xffff0000, v9
	v_and_b32_e32 v53, 0xffff0000, v5
	v_lshlrev_b32_e32 v34, 16, v10
	v_lshlrev_b32_e32 v36, 16, v6
	v_and_b32_e32 v22, 0xffff0000, v10
	v_and_b32_e32 v30, 0xffff0000, v6
	v_lshlrev_b32_e32 v35, 16, v11
	v_lshlrev_b32_e32 v37, 16, v7
	v_and_b32_e32 v23, 0xffff0000, v11
	v_and_b32_e32 v31, 0xffff0000, v7
	v_lshlrev_b32_e32 v55, 16, v1
	v_lshlrev_b32_e32 v54, 16, v0
	v_and_b32_e32 v1, 0xffff0000, v1
	v_and_b32_e32 v0, 0xffff0000, v0
	s_waitcnt vmcnt(4)
	v_mov_b32_e32 v4, v204
	v_mov_b32_e32 v5, v205
	v_mov_b32_e32 v6, v206
	v_mov_b32_e32 v7, v207
	v_mov_b32_e32 v38, v208
	v_mov_b32_e32 v39, v209
	v_mov_b32_e32 v40, v210
	v_mov_b32_e32 v41, v211
	v_mov_b32_e32 v16, v38
	s_waitcnt vmcnt(2)
	v_mov_b32_e32 v8, v212
	v_mov_b32_e32 v9, v213
	v_mov_b32_e32 v10, v214
	v_mov_b32_e32 v11, v215
	v_mov_b32_e32 v46, v216
	v_mov_b32_e32 v47, v217
	v_mov_b32_e32 v48, v218
	v_mov_b32_e32 v49, v219
	v_mov_b32_e32 v18, v46
	v_mov_b32_e32 v19, v48
	v_mov_b32_e32 v17, v40
	v_pk_mul_f32 v[14:15], v[18:19], v[14:15]
	v_mov_b32_e32 v48, v47
	v_pk_fma_f32 v[32:33], v[16:17], v[12:13], v[14:15]
	s_waitcnt vmcnt(0)
	v_mov_b32_e32 v12, v220
	v_mov_b32_e32 v13, v221
	v_mov_b32_e32 v14, v222
	v_mov_b32_e32 v15, v223
	v_mov_b32_e32 v16, v224
	v_mov_b32_e32 v17, v225
	v_mov_b32_e32 v18, v226
	v_mov_b32_e32 v19, v227
	v_mov_b32_e32 v56, v16
	v_mov_b32_e32 v57, v18
	v_pk_fma_f32 v[32:33], v[56:57], v[54:55], v[32:33]
	s_nop 0
	v_mul_f32_e32 v16, 0xbfb8aa3b, v32
	v_exp_f32_e32 v54, v16
	v_mul_f32_e32 v16, 0xbfb8aa3b, v33
	v_exp_f32_e32 v55, v16
	s_nop 0
	v_pk_add_f32 v[54:55], v[54:55], 1.0 op_sel_hi:[1,0]
	s_nop 0
	v_div_scale_f32 v16, s[30:31], v55, v55, v33
	v_rcp_f32_e32 v18, v16
	s_nop 0
	v_fma_f32 v27, -v16, v18, 1.0
	v_fmac_f32_e32 v18, v27, v18
	v_div_scale_f32 v27, vcc, v33, v55, v33
	v_mul_f32_e32 v38, v27, v18
	v_fma_f32 v40, -v16, v38, v27
	v_fmac_f32_e32 v38, v40, v18
	v_fma_f32 v16, -v16, v38, v27
	v_div_fmas_f32 v16, v16, v18, v38
	v_div_fixup_f32 v33, v16, v55, v33
	v_div_scale_f32 v16, s[30:31], v54, v54, v32
	v_rcp_f32_e32 v18, v16
	s_nop 0
	v_fma_f32 v27, -v16, v18, 1.0
	v_fmac_f32_e32 v18, v27, v18
	v_div_scale_f32 v27, vcc, v32, v54, v32
	v_mul_f32_e32 v38, v27, v18
	v_fma_f32 v40, -v16, v38, v27
	v_fmac_f32_e32 v38, v40, v18
	v_fma_f32 v16, -v16, v38, v27
	v_div_fmas_f32 v16, v16, v18, v38
	v_mov_b32_e32 v40, v39
	v_pk_mul_f32 v[38:39], v[48:49], v[52:53]
	v_mov_b32_e32 v18, v17
	v_pk_fma_f32 v[38:39], v[40:41], v[50:51], v[38:39]
	v_div_fixup_f32 v32, v16, v54, v32
	v_pk_fma_f32 v[0:1], v[18:19], v[0:1], v[38:39]
	v_mov_b32_e32 v40, v8
	v_mul_f32_e32 v16, 0xbfb8aa3b, v0
	v_mul_f32_e32 v17, 0xbfb8aa3b, v1
	v_exp_f32_e32 v16, v16
	v_exp_f32_e32 v17, v17
	v_mov_b32_e32 v41, v10
	v_pk_mul_f32 v[36:37], v[40:41], v[36:37]
	v_pk_add_f32 v[16:17], v[16:17], 1.0 op_sel_hi:[1,0]
	s_nop 0
	v_div_scale_f32 v18, s[30:31], v17, v17, v1
	v_rcp_f32_e32 v19, v18
	s_nop 0
	v_fma_f32 v27, -v18, v19, 1.0
	v_fmac_f32_e32 v19, v27, v19
	v_div_scale_f32 v27, vcc, v1, v17, v1
	v_mul_f32_e32 v38, v27, v19
	v_fma_f32 v39, -v18, v38, v27
	v_fmac_f32_e32 v38, v39, v19
	v_fma_f32 v18, -v18, v38, v27
	v_div_fmas_f32 v18, v18, v19, v38
	v_div_fixup_f32 v1, v18, v17, v1
	v_div_scale_f32 v17, s[30:31], v16, v16, v0
	v_rcp_f32_e32 v18, v17
	v_mov_b32_e32 v39, v6
	v_fma_f32 v19, -v17, v18, 1.0
	v_fmac_f32_e32 v18, v19, v18
	v_div_scale_f32 v19, vcc, v0, v16, v0
	v_mul_f32_e32 v27, v19, v18
	v_fma_f32 v38, -v17, v27, v19
	v_fmac_f32_e32 v27, v38, v18
	v_mov_b32_e32 v38, v4
	v_pk_fma_f32 v[34:35], v[38:39], v[34:35], v[36:37]
	v_lshlrev_b32_e32 v37, 16, v3
	v_lshlrev_b32_e32 v36, 16, v2
	v_mov_b32_e32 v38, v12
	v_mov_b32_e32 v39, v14
	v_pk_fma_f32 v[34:35], v[38:39], v[36:37], v[34:35]
	v_fma_f32 v17, -v17, v27, v19
	v_mul_f32_e32 v4, 0xbfb8aa3b, v34
	v_exp_f32_e32 v36, v4
	v_mul_f32_e32 v4, 0xbfb8aa3b, v35
	v_exp_f32_e32 v37, v4
	v_div_fmas_f32 v17, v17, v18, v27
	v_and_b32_e32 v3, 0xffff0000, v3
	v_and_b32_e32 v2, 0xffff0000, v2
	v_pk_add_f32 v[36:37], v[36:37], 1.0 op_sel_hi:[1,0]
	v_mov_b32_e32 v14, v13
	v_div_scale_f32 v4, s[30:31], v37, v37, v35
	v_rcp_f32_e32 v6, v4
	v_div_fixup_f32 v0, v17, v16, v0
	v_mov_b32_e32 v16, v32
	v_mov_b32_e32 v17, v0
	v_fma_f32 v8, -v4, v6, 1.0
	v_fmac_f32_e32 v6, v8, v6
	v_div_scale_f32 v8, vcc, v35, v37, v35
	v_mul_f32_e32 v10, v8, v6
	v_fma_f32 v12, -v4, v10, v8
	v_fmac_f32_e32 v10, v12, v6
	v_fma_f32 v4, -v4, v10, v8
	v_div_fmas_f32 v4, v4, v6, v10
	v_div_fixup_f32 v35, v4, v37, v35
	v_div_scale_f32 v4, s[30:31], v36, v36, v34
	v_rcp_f32_e32 v6, v4
	v_pk_mul_f32 v[16:17], v[16:17], v[16:17]
	v_mov_b32_e32 v18, v33
	v_mov_b32_e32 v19, v1
	v_fma_f32 v8, -v4, v6, 1.0
	v_fmac_f32_e32 v6, v8, v6
	v_div_scale_f32 v8, vcc, v34, v36, v34
	v_mul_f32_e32 v10, v8, v6
	v_fma_f32 v12, -v4, v10, v8
	v_fmac_f32_e32 v10, v12, v6
	v_fma_f32 v4, -v4, v10, v8
	v_div_fmas_f32 v4, v4, v6, v10
	v_mov_b32_e32 v10, v9
	v_div_fixup_f32 v34, v4, v36, v34
	v_mov_b32_e32 v6, v5
	v_pk_mul_f32 v[4:5], v[10:11], v[30:31]
	v_pk_mul_f32 v[18:19], v[18:19], v[18:19]
	v_pk_fma_f32 v[4:5], v[6:7], v[22:23], v[4:5]
	v_mov_b32_e32 v11, 0
	v_pk_fma_f32 v[2:3], v[14:15], v[2:3], v[4:5]
	v_or_b32_e32 v14, 0x800, v45
	v_mul_f32_e32 v4, 0xbfb8aa3b, v2
	v_mul_f32_e32 v5, 0xbfb8aa3b, v3
	v_exp_f32_e32 v4, v4
	v_exp_f32_e32 v5, v5
	v_lshlrev_b32_e32 v128, 1, v14
	v_lshl_add_u64 v[12:13], v[20:21], 0, v[128:129]
	v_pk_add_f32 v[4:5], v[4:5], 1.0 op_sel_hi:[1,0]
	s_nop 0
	v_div_scale_f32 v6, s[30:31], v5, v5, v3
	v_rcp_f32_e32 v7, v6
	s_nop 0
	v_fma_f32 v8, -v6, v7, 1.0
	v_fmac_f32_e32 v7, v8, v7
	v_div_scale_f32 v8, vcc, v3, v5, v3
	v_mul_f32_e32 v9, v8, v7
	v_fma_f32 v10, -v6, v9, v8
	v_fmac_f32_e32 v9, v10, v7
	v_fma_f32 v6, -v6, v9, v8
	v_div_fmas_f32 v6, v6, v7, v9
	v_div_fixup_f32 v3, v6, v5, v3
	v_div_scale_f32 v5, s[30:31], v4, v4, v2
	v_rcp_f32_e32 v6, v5
	v_mov_b32_e32 v10, 0
	v_fma_f32 v7, -v5, v6, 1.0
	v_fmac_f32_e32 v6, v7, v6
	v_div_scale_f32 v7, vcc, v2, v4, v2
	v_mul_f32_e32 v8, v7, v6
	v_fma_f32 v9, -v5, v8, v7
	v_fmac_f32_e32 v8, v9, v6
	v_fma_f32 v5, -v5, v8, v7
	v_div_fmas_f32 v5, v5, v6, v8
	v_div_fixup_f32 v2, v5, v4, v2
	v_add_f32_e32 v8, v16, v17
	v_mov_b32_e32 v4, v34
	v_mov_b32_e32 v5, v2
	v_add_f32_e32 v8, v8, v18
	v_pk_mul_f32 v[4:5], v[4:5], v[4:5]
	v_add_f32_e32 v8, v8, v19
	v_mov_b32_e32 v6, v35
	v_mov_b32_e32 v7, v3
	v_add_f32_e32 v4, v8, v4
	v_pk_mul_f32 v[6:7], v[6:7], v[6:7]
	v_add_f32_e32 v4, v4, v5
	v_add_f32_e32 v4, v4, v6
	v_add_f32_e32 v4, v4, v7
	s_nop 1
	v_add_f32_dpp v4, v4, v4 quad_perm:[1,0,3,2] row_mask:0xf bank_mask:0xf bound_ctrl:1
	s_nop 1
	v_add_f32_dpp v4, v4, v4 quad_perm:[2,3,0,1] row_mask:0xf bank_mask:0xf bound_ctrl:1
	s_nop 1
	v_add_f32_dpp v4, v4, v4 row_half_mirror row_mask:0xf bank_mask:0xf bound_ctrl:1
	s_nop 1
	v_add_f32_dpp v4, v4, v4 row_mirror row_mask:0xf bank_mask:0xf bound_ctrl:1
	v_add_f32_e32 v4, 0x358637bd, v4
	v_cmp_gt_f32_e32 vcc, s95, v4
	v_mul_f32_e32 v5, 0x4b800000, v4
	s_nop 0
	v_cndmask_b32_e32 v4, v4, v5, vcc
	v_rsq_f32_e32 v4, v4
	s_nop 0
	v_mul_f32_e32 v5, 0x45800000, v4
	v_cndmask_b32_e32 v4, v4, v5, vcc
	v_pk_mul_f32 v[6:7], v[32:33], v[4:5] op_sel_hi:[1,0]
	v_pk_mul_f32 v[0:1], v[0:1], v[4:5] op_sel_hi:[1,0]
	v_pk_mul_f32 v[8:9], v[34:35], v[4:5] op_sel_hi:[1,0]
	v_pk_mul_f32 v[2:3], v[2:3], v[4:5] op_sel_hi:[1,0]
	v_and_b32_sdwa v5, v6, v150 dst_sel:DWORD dst_unused:UNUSED_PAD src0_sel:WORD_1 src1_sel:DWORD
	v_and_b32_sdwa v4, v7, v150 dst_sel:DWORD dst_unused:UNUSED_PAD src0_sel:WORD_1 src1_sel:DWORD
	v_add3_u32 v5, v6, v5, s26
	v_and_b32_sdwa v6, v1, v150 dst_sel:DWORD dst_unused:UNUSED_PAD src0_sel:WORD_1 src1_sel:DWORD
	v_add3_u32 v4, v7, v4, s26
	v_and_b32_sdwa v7, v0, v150 dst_sel:DWORD dst_unused:UNUSED_PAD src0_sel:WORD_1 src1_sel:DWORD
	v_add3_u32 v1, v1, v6, s26
	v_add3_u32 v0, v0, v7, s26
	v_and_b32_e32 v1, 0xffff0000, v1
	v_and_b32_sdwa v6, v3, v150 dst_sel:DWORD dst_unused:UNUSED_PAD src0_sel:WORD_1 src1_sel:DWORD
	v_and_b32_e32 v0, 0xffff0000, v0
	v_or_b32_sdwa v1, v1, v4 dst_sel:DWORD dst_unused:UNUSED_PAD src0_sel:DWORD src1_sel:WORD_1
	v_and_b32_sdwa v4, v9, v150 dst_sel:DWORD dst_unused:UNUSED_PAD src0_sel:WORD_1 src1_sel:DWORD
	v_and_b32_sdwa v7, v2, v150 dst_sel:DWORD dst_unused:UNUSED_PAD src0_sel:WORD_1 src1_sel:DWORD
	v_add3_u32 v3, v3, v6, s26
	v_or_b32_sdwa v0, v0, v5 dst_sel:DWORD dst_unused:UNUSED_PAD src0_sel:DWORD src1_sel:WORD_1
	v_and_b32_sdwa v5, v8, v150 dst_sel:DWORD dst_unused:UNUSED_PAD src0_sel:WORD_1 src1_sel:DWORD
	v_add3_u32 v4, v9, v4, s26
	v_add3_u32 v2, v2, v7, s26
	v_and_b32_e32 v3, 0xffff0000, v3
	v_add3_u32 v5, v8, v5, s26
	v_and_b32_e32 v2, 0xffff0000, v2
	v_or_b32_sdwa v3, v3, v4 dst_sel:DWORD dst_unused:UNUSED_PAD src0_sel:DWORD src1_sel:WORD_1
	v_add_co_u32_e32 v4, vcc, 0x25800000, v28
	v_or_b32_sdwa v2, v2, v5 dst_sel:DWORD dst_unused:UNUSED_PAD src0_sel:DWORD src1_sel:WORD_1
	s_nop 0
	v_addc_co_u32_e32 v5, vcc, 0, v29, vcc
	global_store_dwordx4 v[4:5], v[0:3], off
	global_load_dwordx4 v[0:3], v[12:13], off
	v_mov_b32_e32 v4, 0
	v_mov_b32_e32 v8, 0
	v_mov_b32_e32 v9, 0
	s_and_saveexec_b64 s[54:55], s[40:41]
	s_cbranch_execz .LBB0_344
	v_add_co_u32_e32 v6, vcc, 0xffffd000, v12
	s_nop 1
	v_addc_co_u32_e32 v7, vcc, -1, v13, vcc
	global_load_dwordx4 v[8:11], v[6:7], off offset:-2560
